# P3 K-split ratios and epilogue scales computed once in the GEMM set-up: no loads/waits inside the K-loop rescale block or in the epilogue rows
# baseline (speedup 1.0000x reference)
; __device__ __forceinline__ float ss_get(const ss_t* p) { const ss_t v = *p; return (float)(unsigned)(v >> 32) + (float)(unsigned)v * 2.3283064365386963e-10f; }
; #define PG8_WAIT_V(n) asm volatile("s_waitcnt vmcnt(" #n ")" ::: "memory")
; #define PG8_BAR __builtin_amdgcn_s_barrier()
;     __device__ __forceinline__ void mid(f32x4 (&acc)[2][2][4][2], const Unit& u, int wr, int wc, int fr, int fq) const {
;     ...
;                 const float ra = 1.0f / sqrtf(ss_get(ssa + row) * (1.0f / 1024.f) + 1e-6f), rbi = sqrtf(ss_get(ssb + row) * (1.0f / 1024.f) + 1e-6f); const float ratio = ra * rbi;
; template <class Epi, class Sched, bool ALIGN_EPI = false, bool SP2 = false>
; __device__ __forceinline__ void gemm_phase(PG8_LAS unsigned char* lds, const Gemm g, const Sched& S, const Epi& E) {
;     ...
;     for (int i = 0; i < 2; ++i) { int R, C; stage_rc(tid * 16 + i * 8192, R, C); const int Rb = Epi::PERM ? ((R & ~31) + perm32(R & 31)) : R;
;         voffA[i] = (unsigned)(R * K + C) * 2u; voffB[i] = (unsigned)(Rb * K + C) * 2u; }
;     const size_t kstep = (size_t)(BK * 2);
;     const size_t hstep = (size_t)HALF * K * 2;
;     const size_t tstep = 2 * hstep;
;     const unsigned ldsw = (unsigned)wid * 1024u;
;     const int aoff = lds_byte(wr * 64 + fr, fq * 8), boff = lds_byte(wc * 32 + fr, fq * 8);
;     ...
;     Unit cur, nxt; int ui = 0;
;     if (!S.next(0, cur)) return;
;     f32x4 acc[2][2][4][2];
; #pragma unroll
;     for (int a = 0; a < 2; ++a)
; #pragma unroll
;         for (int b = 0; b < 2; ++b)
; #pragma unroll
;             for (int m = 0; m < 4; ++m)
; #pragma unroll
;                 for (int n = 0; n < 2; ++n) acc[a][b][m][n] = (f32x4){0.f, 0.f, 0.f, 0.f};
;     bf16x8 At[4][2], B0[2][2], B1[2][2];
;     const char* cA = (const char*)g.A + (size_t)cur.pm * tstep; const char* cB = (const char*)g.Bt + (size_t)cur.pn * tstep;
;     S.a_ready(cur);
;     if constexpr (SP2) {
;         PG8_STAGE(PG8_SB(0, 0), cB, voffB); PG8_STAGE(PG8_SB(0, 1), cB + hstep, voffB); PG8_STAGE(PG8_SA(0, 0), cA, voffA); PG8_STAGE(PG8_SA(0, 1), cA + hstep, voffA);
;         if (wr == 1) PG8_BAR;
;         PG8_WAIT_V(2); PG8_BAR;
;         PG8_STAGE(PG8_SB(1, 0), cB + kstep, voffB); PG8_STAGE(PG8_SA(1, 0), cA + kstep, voffA); PG8_STAGE(PG8_SB(1, 1), cB + hstep + kstep, voffB);
.LBB0_918:
	s_andn2_b64 vcc, exec, s[2:3]
	v_readlane_b32 s2, v248, 19
	v_readlane_b32 s3, v248, 20
	s_nop 1
	v_cndmask_b32_e64 v0, 0, 1, s[2:3]
	v_cmp_ne_u32_e64 s[38:39], 1, v0
	s_cbranch_vccnz .LBB0_951
	v_mov_b32_e32 v11, v204
	s_and_b64 vcc, exec, s[38:39]
	v_readfirstlane_b32 s2, v11
	s_cbranch_vccnz .LBB0_951
	v_readlane_b32 s100, v250, 59
	v_bfe_u32 v252, v204, 8, 1
	v_and_b32_e32 v253, 15, v204
	v_lshl_or_b32 v252, v252, 6, v253
	v_add_u32_e32 v252, s100, v252
	v_mov_b32_e32 v253, 0
	v_lshlrev_b64 v[252:253], 3, v[252:253]
	v_lshl_add_u64 v[98:99], v[252:253], 0, s[6:7]
	v_lshl_add_u64 v[252:253], v[252:253], 0, s[8:9]
	global_load_dwordx2 v[100:101], v[98:99], off
	global_load_dwordx2 v[102:103], v[98:99], off offset:128
	global_load_dwordx2 v[104:105], v[98:99], off offset:256
	global_load_dwordx2 v[106:107], v[98:99], off offset:384
	global_load_dwordx2 v[108:109], v[98:99], off offset:1024
	global_load_dwordx2 v[110:111], v[98:99], off offset:1152
	global_load_dwordx2 v[112:113], v[98:99], off offset:1280
	global_load_dwordx2 v[114:115], v[98:99], off offset:1408
	global_load_dwordx2 v[116:117], v[252:253], off
	global_load_dwordx2 v[118:119], v[252:253], off offset:128
	global_load_dwordx2 v[120:121], v[252:253], off offset:256
	global_load_dwordx2 v[122:123], v[252:253], off offset:384
	global_load_dwordx2 v[124:125], v[252:253], off offset:1024
	global_load_dwordx2 v[126:127], v[252:253], off offset:1152
	global_load_dwordx2 v[128:129], v[252:253], off offset:1280
	global_load_dwordx2 v[130:131], v[252:253], off offset:1408
	v_lshlrev_b32_e32 v0, 4, v11
	s_waitcnt lgkmcnt(0)
	v_add_u32_e32 v1, 0x2000, v0
	v_ashrrev_i32_e32 v3, 31, v1
	v_lshrrev_b32_e32 v3, 22, v3
	v_add_u32_e32 v3, v1, v3
	v_ashrrev_i32_e32 v3, 10, v3
	v_mul_i32_i24_e32 v4, 0x400, v3
	v_sub_u32_e32 v1, v1, v4
	v_lshrrev_b32_e32 v4, 4, v1
	v_bitop3_b32 v1, v4, v1, 32 bitop3:0x6c
	v_ashrrev_i32_e32 v4, 31, v1
	v_lshrrev_b32_e32 v4, 26, v4
	v_add_u32_e32 v4, v1, v4
	v_lshlrev_b32_e32 v5, 3, v3
	v_ashrrev_i32_e32 v6, 6, v4
	v_and_b32_e32 v5, -16, v5
	v_add_u32_e32 v5, v6, v5
	v_and_b32_e32 v7, 3, v6
	s_mov_b32 s10, 0xfffe0
	v_lshrrev_b32_e32 v8, 2, v5
	v_lshlrev_b32_e32 v9, 1, v5
	v_and_b32_e32 v4, 0xc0, v4
	v_and_or_b32 v7, v5, s10, v7
	v_and_b32_e32 v8, 4, v8
	v_and_b32_e32 v9, 24, v9
	v_sub_u32_e32 v1, v1, v4
	v_or3_b32 v8, v7, v8, v9
	v_lshlrev_b32_e32 v7, 5, v3
	v_ashrrev_i16_sdwa v1, v207, sext(v1) dst_sel:DWORD dst_unused:UNUSED_PAD src0_sel:DWORD src1_sel:BYTE_0
	v_and_b32_e32 v9, 32, v7
	v_bfe_i32 v7, v1, 0, 16
	v_add_lshl_u32 v1, v9, v7, 1
	v_lshl_add_u32 v156, v8, 12, v1
	v_lshl_add_u32 v158, v5, 12, v1
	v_bfe_i32 v1, v11, 27, 1
	v_lshrrev_b32_e32 v1, 22, v1
	v_add_u32_e32 v1, v0, v1
	v_and_b32_e32 v1, 0xfffffc00, v1
	v_sub_u32_e32 v0, v0, v1
	v_lshrrev_b32_e32 v1, 4, v0
	v_ashrrev_i32_e32 v4, 31, v11
	v_bitop3_b32 v0, v1, v0, 32 bitop3:0x6c
	v_lshrrev_b32_e32 v4, 26, v4
	v_ashrrev_i32_e32 v1, 31, v0
	v_add_u32_e32 v4, v11, v4
	v_lshrrev_b32_e32 v1, 26, v1
	v_ashrrev_i32_e32 v9, 6, v4
	v_add_u32_e32 v1, v0, v1
	v_lshlrev_b32_e32 v4, 3, v9
	v_ashrrev_i32_e32 v8, 6, v1
	v_and_b32_e32 v4, -16, v4
	v_add_u32_e32 v4, v8, v4
	v_and_b32_e32 v5, 3, v8
	v_lshrrev_b32_e32 v10, 2, v4
	v_lshlrev_b32_e32 v12, 1, v4
	v_and_b32_e32 v1, 0xc0, v1
	s_ashr_i32 s3, s2, 6
	v_and_or_b32 v5, v4, s10, v5
	v_and_b32_e32 v10, 4, v10
	v_and_b32_e32 v12, 24, v12
	v_sub_u32_e32 v0, v0, v1
	s_ashr_i32 s14, s2, 8
	s_lshl_b32 s50, s3, 10
	v_or3_b32 v5, v5, v10, v12
	v_lshlrev_b32_e32 v10, 5, v9
	v_ashrrev_i16_sdwa v0, v207, sext(v0) dst_sel:DWORD dst_unused:UNUSED_PAD src0_sel:DWORD src1_sel:BYTE_0
	v_readlane_b32 s10, v247, 12
	v_and_b32_e32 v12, 32, v10
	v_bfe_i32 v10, v0, 0, 16
	v_readlane_b32 s11, v247, 13
	s_add_u32 s10, s52, s10
	v_add_lshl_u32 v0, v12, v10, 1
	s_addc_u32 s11, s53, s11
	s_add_i32 s51, s50, 0
	v_lshl_add_u32 v172, v5, 12, v0
	s_add_i32 m0, s51, 0x10000
	v_lshl_add_u32 v174, v4, 12, v0
	global_load_lds_dwordx4 v172, s[10:11]
	s_add_i32 m0, s51, 0x12000
	s_add_u32 s12, s10, 0x80000
	global_load_lds_dwordx4 v156, s[10:11]
	s_addc_u32 s13, s11, 0
	s_add_i32 m0, s51, 0x14000
	s_add_i32 s54, s51, 0x2000
	global_load_lds_dwordx4 v172, s[12:13]
	s_add_i32 m0, s51, 0x16000
	s_add_i32 s55, s51, 0x4000
	global_load_lds_dwordx4 v156, s[12:13]
	s_mov_b32 m0, s51
	v_readlane_b32 s12, v248, 21
	global_load_lds_dwordx4 v174, s[88:89]
	s_mov_b32 m0, s54
	v_readlane_b32 s13, v248, 22
	global_load_lds_dwordx4 v158, s[88:89]
	s_mov_b32 m0, s55
	s_add_i32 s56, s51, 0x6000
	v_mov_b32_e32 v173, v2
	s_nop 0
	global_load_lds_dwordx4 v174, s[12:13]
	s_mov_b32 m0, s56
	v_mov_b32_e32 v157, v2
	global_load_lds_dwordx4 v158, s[12:13]
	s_cmp_eq_u32 s14, 1
	v_lshl_add_u64 v[0:1], s[10:11], 0, v[172:173]
	s_cselect_b64 s[12:13], -1, 0
	s_cmp_lg_u32 s14, 1
	v_lshl_add_u64 v[4:5], s[10:11], 0, v[156:157]
	s_cbranch_scc1 .LBB0_922
	s_barrier
; __device__ __forceinline__ float ss_get(const ss_t* p) { const ss_t v = *p; return (float)(unsigned)(v >> 32) + (float)(unsigned)v * 2.3283064365386963e-10f; }
; #define PG8_STAGE(bufoff, gbase, voff) do { _Pragma("unroll") for (int _i = 0; _i < 2; ++_i) \
;         __builtin_amdgcn_global_load_lds((const unsigned*)((const char*)(gbase) + (voff)[_i]), (PG8_LAS unsigned*)(lds + (bufoff) + ldsw + _i * 8192), 16, 0, 0); } while (0)
; #define PG8_WAIT_V(n) asm volatile("s_waitcnt vmcnt(" #n ")" ::: "memory")
; #define PG8_BAR __builtin_amdgcn_s_barrier()
;     __device__ __forceinline__ void mid(f32x4 (&acc)[2][2][4][2], const Unit& u, int wr, int wc, int fr, int fq) const {
;     ...
;                 const float ra = 1.0f / sqrtf(ss_get(ssa + row) * (1.0f / 1024.f) + 1e-6f), rbi = sqrtf(ss_get(ssb + row) * (1.0f / 1024.f) + 1e-6f); const float ratio = ra * rbi;
; #pragma unroll
;                 for (int bj = 0; bj < 2; ++bj)
; #pragma unroll
;                     for (int n = 0; n < 2; ++n) acc[ai][bj][m][n] = acc[ai][bj][m][n] * ratio; }
; template <class Epi, class Sched, bool ALIGN_EPI = false, bool SP2 = false>
; __device__ __forceinline__ void gemm_phase(PG8_LAS unsigned char* lds, const Gemm g, const Sched& S, const Epi& E) {
;     ...
;         PG8_STAGE(PG8_SB(0, 0), cB, voffB); PG8_STAGE(PG8_SB(0, 1), cB + hstep, voffB); PG8_STAGE(PG8_SA(0, 0), cA, voffA); PG8_STAGE(PG8_SA(0, 1), cA + hstep, voffA);
;         if (wr == 1) PG8_BAR;
;         PG8_WAIT_V(2); PG8_BAR;
;         PG8_STAGE(PG8_SB(1, 0), cB + kstep, voffB); PG8_STAGE(PG8_SA(1, 0), cA + kstep, voffA); PG8_STAGE(PG8_SB(1, 1), cB + hstep + kstep, voffB);
;         PG8_WAIT_V(6); PG8_BAR;
.LBB0_922:
	v_bfe_u32 v17, v11, 4, 2
	v_and_b32_e32 v16, 15, v11
	v_lshlrev_b32_e32 v19, 4, v17
	v_lshlrev_b32_e32 v11, 2, v11
	s_lshl_b32 s3, s3, 5
	v_mov_b32_e32 v175, v2
	v_lshl_or_b32 v18, s14, 6, v16
	v_lshl_or_b32 v16, v16, 6, v19
	s_lshl_b32 s14, s14, 13
	v_and_b32_e32 v11, 32, v11
	s_and_b32 s3, s3, 0x60
	s_add_i32 m0, s51, 0x18000
	v_lshl_add_u64 v[0:1], v[0:1], 0, s[28:29]
	v_lshl_add_u64 v[12:13], s[88:89], 0, v[174:175]
	v_mov_b32_e32 v159, v2
	v_bitop3_b32 v19, v16, s14, v11 bitop3:0xde
	s_lshl_b32 s14, s3, 7
	s_waitcnt vmcnt(2)
	s_barrier
	global_load_lds_dwordx4 v[0:1], off
	v_lshl_add_u64 v[0:1], v[4:5], 0, s[28:29]
	s_add_i32 m0, s51, 0x1a000
	s_add_i32 s57, s51, 0x8000
	s_add_i32 s58, s51, 0xa000
	v_lshl_add_u64 v[14:15], s[88:89], 0, v[158:159]
	v_bitop3_b32 v192, v16, s14, v11 bitop3:0xde
	global_load_lds_dwordx4 v[0:1], off
	v_lshl_add_u64 v[0:1], v[12:13], 0, s[28:29]
	s_mov_b32 m0, s57
	s_add_u32 s14, s10, 0x80080
	global_load_lds_dwordx4 v[0:1], off
	v_lshl_add_u64 v[0:1], v[14:15], 0, s[28:29]
	s_mov_b32 m0, s58
	s_addc_u32 s15, s11, 0
	global_load_lds_dwordx4 v[0:1], off
	s_add_i32 m0, s51, 0x1c000
	v_lshl_add_u64 v[0:1], s[14:15], 0, v[172:173]
	global_load_lds_dwordx4 v[0:1], off
	v_lshl_add_u64 v[0:1], s[14:15], 0, v[156:157]
	s_add_i32 m0, s51, 0x1e000
	s_cmpk_lt_u32 s2, 0x100
	global_load_lds_dwordx4 v[0:1], off
	v_lshlrev_b32_e32 v0, 15, v9
	v_and_b32_e32 v0, 0xffff0000, v0
	v_readlane_b32 s2, v250, 59
	v_lshl_add_u32 v0, v8, 12, v0
	v_and_b32_e32 v1, 1, v9
	v_add_u32_e32 v193, s2, v18
	v_lshl_or_b32 v194, v17, 3, s3
	v_lshl_or_b32 v0, v1, 6, v0
	v_readlane_b32 s2, v247, 16
	v_lshl_add_u32 v0, v10, 1, v0
	v_mov_b32_e32 v1, v2
	v_readlane_b32 s3, v247, 17
	s_waitcnt vmcnt(6)
	v_readlane_b32 s36, v247, 18
	s_cselect_b64 s[14:15], -1, 0
	v_cvt_f32_u32_e32 v96, v101
	v_cvt_f32_u32_e32 v97, v100
	v_fmac_f32_e32 v96, 0x2f800000, v97
	v_fmamk_f32 v96, v96, 0x3a800000, v205
	v_cvt_f32_u32_e32 v98, v117
	v_cvt_f32_u32_e32 v99, v116
	v_fmac_f32_e32 v98, 0x2f800000, v99
	v_fmamk_f32 v98, v98, 0x3a800000, v205
	v_rsq_f32_e32 v96, v96
	v_sqrt_f32_e32 v97, v98
	v_rsq_f32_e32 v240, v98
	s_nop 0
	v_mul_f32_e32 v160, v96, v97
	v_cvt_f32_u32_e32 v96, v103
	v_cvt_f32_u32_e32 v97, v102
	v_fmac_f32_e32 v96, 0x2f800000, v97
	v_fmamk_f32 v96, v96, 0x3a800000, v205
	v_cvt_f32_u32_e32 v98, v119
	v_cvt_f32_u32_e32 v99, v118
	v_fmac_f32_e32 v98, 0x2f800000, v99
	v_fmamk_f32 v98, v98, 0x3a800000, v205
	v_rsq_f32_e32 v96, v96
	v_sqrt_f32_e32 v97, v98
	v_rsq_f32_e32 v241, v98
	s_nop 0
	v_mul_f32_e32 v161, v96, v97
	v_cvt_f32_u32_e32 v96, v105
	v_cvt_f32_u32_e32 v97, v104
	v_fmac_f32_e32 v96, 0x2f800000, v97
	v_fmamk_f32 v96, v96, 0x3a800000, v205
	v_cvt_f32_u32_e32 v98, v121
	v_cvt_f32_u32_e32 v99, v120
	v_fmac_f32_e32 v98, 0x2f800000, v99
	v_fmamk_f32 v98, v98, 0x3a800000, v205
	v_rsq_f32_e32 v96, v96
	v_sqrt_f32_e32 v97, v98
	v_rsq_f32_e32 v242, v98
	s_nop 0
	v_mul_f32_e32 v162, v96, v97
	v_cvt_f32_u32_e32 v96, v107
	v_cvt_f32_u32_e32 v97, v106
	v_fmac_f32_e32 v96, 0x2f800000, v97
	v_fmamk_f32 v96, v96, 0x3a800000, v205
	v_cvt_f32_u32_e32 v98, v123
	v_cvt_f32_u32_e32 v99, v122
	v_fmac_f32_e32 v98, 0x2f800000, v99
	v_fmamk_f32 v98, v98, 0x3a800000, v205
	v_rsq_f32_e32 v96, v96
	v_sqrt_f32_e32 v97, v98
	v_rsq_f32_e32 v243, v98
	s_nop 0
	v_mul_f32_e32 v163, v96, v97
	v_cvt_f32_u32_e32 v96, v109
	v_cvt_f32_u32_e32 v97, v108
	v_fmac_f32_e32 v96, 0x2f800000, v97
	v_fmamk_f32 v96, v96, 0x3a800000, v205
	v_cvt_f32_u32_e32 v98, v125
	v_cvt_f32_u32_e32 v99, v124
	v_fmac_f32_e32 v98, 0x2f800000, v99
	v_fmamk_f32 v98, v98, 0x3a800000, v205
	v_rsq_f32_e32 v96, v96
	v_sqrt_f32_e32 v97, v98
	v_rsq_f32_e32 v244, v98
	s_nop 0
	v_mul_f32_e32 v164, v96, v97
	v_cvt_f32_u32_e32 v96, v111
	v_cvt_f32_u32_e32 v97, v110
	v_fmac_f32_e32 v96, 0x2f800000, v97
	v_fmamk_f32 v96, v96, 0x3a800000, v205
	v_cvt_f32_u32_e32 v98, v127
	v_cvt_f32_u32_e32 v99, v126
	v_fmac_f32_e32 v98, 0x2f800000, v99
	v_fmamk_f32 v98, v98, 0x3a800000, v205
	v_rsq_f32_e32 v96, v96
	v_sqrt_f32_e32 v97, v98
	v_rsq_f32_e32 v245, v98
	s_nop 0
	v_mul_f32_e32 v165, v96, v97
	v_cvt_f32_u32_e32 v96, v113
	v_cvt_f32_u32_e32 v97, v112
	v_fmac_f32_e32 v96, 0x2f800000, v97
	v_fmamk_f32 v96, v96, 0x3a800000, v205
	v_cvt_f32_u32_e32 v98, v129
	v_cvt_f32_u32_e32 v99, v128
	v_fmac_f32_e32 v98, 0x2f800000, v99
	v_fmamk_f32 v98, v98, 0x3a800000, v205
	v_rsq_f32_e32 v96, v96
	v_sqrt_f32_e32 v97, v98
	v_rsq_f32_e32 v246, v98
	s_nop 0
	v_mul_f32_e32 v166, v96, v97
	v_cvt_f32_u32_e32 v96, v115
	v_cvt_f32_u32_e32 v97, v114
	v_fmac_f32_e32 v96, 0x2f800000, v97
	v_fmamk_f32 v96, v96, 0x3a800000, v205
	v_cvt_f32_u32_e32 v98, v131
	v_cvt_f32_u32_e32 v99, v130
	v_fmac_f32_e32 v98, 0x2f800000, v99
	v_fmamk_f32 v98, v98, 0x3a800000, v205
	v_rsq_f32_e32 v96, v96
	v_sqrt_f32_e32 v97, v98
	v_rsq_f32_e32 v252, v98
	s_nop 0
	v_mul_f32_e32 v167, v96, v97
	v_lshl_add_u64 v[176:177], s[2:3], 0, v[0:1]
	v_lshlrev_b32_e32 v0, 15, v3
	v_and_b32_e32 v0, 0xffff0000, v0
	v_lshl_add_u32 v0, v6, 12, v0
	v_and_b32_e32 v1, 1, v3
	v_lshl_or_b32 v0, v1, 6, v0
	v_lshl_add_u32 v0, v7, 1, v0
	v_mov_b32_e32 v1, v2
	s_mov_b32 s59, 0
	v_cmp_eq_u32_e64 s[40:41], 0, v17
	v_lshl_add_u64 v[178:179], s[2:3], 0, v[0:1]
	v_add_u32_e32 v195, 0, v19
	v_readlane_b32 s37, v247, 19
	v_readlane_b32 s42, v248, 25
	s_barrier
	v_readlane_b32 s43, v248, 26
	s_branch .LBB0_925

; __device__ __forceinline__ float ss_get(const ss_t* p) { const ss_t v = *p; return (float)(unsigned)(v >> 32) + (float)(unsigned)v * 2.3283064365386963e-10f; }
;     __device__ __forceinline__ void mid(f32x4 (&acc)[2][2][4][2], const Unit& u, int wr, int wc, int fr, int fq) const {
;         int row0 = u.pm * BM + wr * 64 + fr; asm volatile("" : "+v"(row0));
; #pragma unroll
;         for (int ai = 0; ai < 2; ++ai)
; #pragma unroll
;             for (int m = 0; m < 4; ++m) { const int row = row0 + ai * HALF + m * 16;
;                 const float ra = 1.0f / sqrtf(ss_get(ssa + row) * (1.0f / 1024.f) + 1e-6f), rbi = sqrtf(ss_get(ssb + row) * (1.0f / 1024.f) + 1e-6f); const float ratio = ra * rbi;
; #pragma unroll
;                 for (int bj = 0; bj < 2; ++bj)
; #pragma unroll
;                     for (int n = 0; n < 2; ++n) acc[ai][bj][m][n] = acc[ai][bj][m][n] * ratio; }
.LBB0_927:
	s_cmpk_lg_i32 s46, 0x800
	s_cbranch_scc1 .LBB0_926
	v_mul_f32_e32 v116, v160, v116
	v_mul_f32_e32 v117, v160, v117
	v_mul_f32_e32 v118, v160, v118
	v_mul_f32_e32 v119, v160, v119
	v_mul_f32_e32 v120, v160, v120
	v_mul_f32_e32 v121, v160, v121
	v_mul_f32_e32 v122, v160, v122
	v_mul_f32_e32 v123, v160, v123
	v_mul_f32_e32 v124, v160, v124
	v_mul_f32_e32 v125, v160, v125
	v_mul_f32_e32 v126, v160, v126
	v_mul_f32_e32 v127, v160, v127
	v_mul_f32_e32 v128, v160, v128
	v_mul_f32_e32 v129, v160, v129
	v_mul_f32_e32 v130, v160, v130
	v_mul_f32_e32 v131, v160, v131
	v_mul_f32_e32 v100, v161, v100
	v_mul_f32_e32 v101, v161, v101
	v_mul_f32_e32 v102, v161, v102
	v_mul_f32_e32 v103, v161, v103
	v_mul_f32_e32 v104, v161, v104
	v_mul_f32_e32 v105, v161, v105
	v_mul_f32_e32 v106, v161, v106
	v_mul_f32_e32 v107, v161, v107
	v_mul_f32_e32 v108, v161, v108
	v_mul_f32_e32 v109, v161, v109
	v_mul_f32_e32 v110, v161, v110
	v_mul_f32_e32 v111, v161, v111
	v_mul_f32_e32 v112, v161, v112
	v_mul_f32_e32 v113, v161, v113
	v_mul_f32_e32 v114, v161, v114
	v_mul_f32_e32 v115, v161, v115
	v_mul_f32_e32 v84, v162, v84
	v_mul_f32_e32 v85, v162, v85
	v_mul_f32_e32 v86, v162, v86
	v_mul_f32_e32 v87, v162, v87
	v_mul_f32_e32 v88, v162, v88
	v_mul_f32_e32 v89, v162, v89
	v_mul_f32_e32 v90, v162, v90
	v_mul_f32_e32 v91, v162, v91
	v_mul_f32_e32 v92, v162, v92
	v_mul_f32_e32 v93, v162, v93
	v_mul_f32_e32 v94, v162, v94
	v_mul_f32_e32 v95, v162, v95
	v_mul_f32_e32 v96, v162, v96
	v_mul_f32_e32 v97, v162, v97
	v_mul_f32_e32 v98, v162, v98
	v_mul_f32_e32 v99, v162, v99
	v_mul_f32_e32 v68, v163, v68
	v_mul_f32_e32 v69, v163, v69
	v_mul_f32_e32 v70, v163, v70
	v_mul_f32_e32 v71, v163, v71
	v_mul_f32_e32 v72, v163, v72
	v_mul_f32_e32 v73, v163, v73
	v_mul_f32_e32 v74, v163, v74
	v_mul_f32_e32 v75, v163, v75
	v_mul_f32_e32 v76, v163, v76
	v_mul_f32_e32 v77, v163, v77
	v_mul_f32_e32 v78, v163, v78
	v_mul_f32_e32 v79, v163, v79
	v_mul_f32_e32 v80, v163, v80
	v_mul_f32_e32 v81, v163, v81
	v_mul_f32_e32 v82, v163, v82
	v_mul_f32_e32 v83, v163, v83
	v_mul_f32_e32 v52, v164, v52
	v_mul_f32_e32 v53, v164, v53
	v_mul_f32_e32 v54, v164, v54
	v_mul_f32_e32 v55, v164, v55
	v_mul_f32_e32 v56, v164, v56
	v_mul_f32_e32 v57, v164, v57
	v_mul_f32_e32 v58, v164, v58
	v_mul_f32_e32 v59, v164, v59
	v_mul_f32_e32 v60, v164, v60
	v_mul_f32_e32 v61, v164, v61
	v_mul_f32_e32 v62, v164, v62
	v_mul_f32_e32 v63, v164, v63
	v_mul_f32_e32 v64, v164, v64
	v_mul_f32_e32 v65, v164, v65
	v_mul_f32_e32 v66, v164, v66
	v_mul_f32_e32 v67, v164, v67
	v_mul_f32_e32 v36, v165, v36
	v_mul_f32_e32 v37, v165, v37
	v_mul_f32_e32 v38, v165, v38
	v_mul_f32_e32 v39, v165, v39
	v_mul_f32_e32 v40, v165, v40
	v_mul_f32_e32 v41, v165, v41
	v_mul_f32_e32 v42, v165, v42
	v_mul_f32_e32 v43, v165, v43
	v_mul_f32_e32 v44, v165, v44
	v_mul_f32_e32 v45, v165, v45
	v_mul_f32_e32 v46, v165, v46
	v_mul_f32_e32 v47, v165, v47
	v_mul_f32_e32 v48, v165, v48
	v_mul_f32_e32 v49, v165, v49
	v_mul_f32_e32 v50, v165, v50
	v_mul_f32_e32 v51, v165, v51
	v_mul_f32_e32 v20, v166, v20
	v_mul_f32_e32 v21, v166, v21
	v_mul_f32_e32 v22, v166, v22
	v_mul_f32_e32 v23, v166, v23
	v_mul_f32_e32 v24, v166, v24
	v_mul_f32_e32 v25, v166, v25
	v_mul_f32_e32 v26, v166, v26
	v_mul_f32_e32 v27, v166, v27
	v_mul_f32_e32 v28, v166, v28
	v_mul_f32_e32 v29, v166, v29
	v_mul_f32_e32 v30, v166, v30
	v_mul_f32_e32 v31, v166, v31
	v_mul_f32_e32 v32, v166, v32
	v_mul_f32_e32 v33, v166, v33
	v_mul_f32_e32 v34, v166, v34
	v_mul_f32_e32 v35, v166, v35
	v_mul_f32_e32 v4, v167, v4
	v_mul_f32_e32 v5, v167, v5
	v_mul_f32_e32 v6, v167, v6
	v_mul_f32_e32 v7, v167, v7
	v_mul_f32_e32 v8, v167, v8
	v_mul_f32_e32 v9, v167, v9
	v_mul_f32_e32 v10, v167, v10
	v_mul_f32_e32 v11, v167, v11
	v_mul_f32_e32 v12, v167, v12
	v_mul_f32_e32 v13, v167, v13
	v_mul_f32_e32 v14, v167, v14
	v_mul_f32_e32 v15, v167, v15
	v_mul_f32_e32 v16, v167, v16
	v_mul_f32_e32 v17, v167, v17
	v_mul_f32_e32 v18, v167, v18
	v_mul_f32_e32 v19, v167, v19
	s_branch .LBB0_926

; __device__ __forceinline__ void ss_add(ss_t* p, float sq) { const float fl = floorf(sq); const unsigned hi = (unsigned)fl, lo = (unsigned)((sq - fl) * 4294967296.0f); atomicAdd(p, ((ss_t)hi << 32) | (ss_t)lo); }
; __device__ __forceinline__ float ss_get(const ss_t* p) { const ss_t v = *p; return (float)(unsigned)(v >> 32) + (float)(unsigned)v * 2.3283064365386963e-10f; }
;     __device__ __forceinline__ void operator()(const f32x4 (&acc)[2][2][4][2], const Unit& u, int wr, int wc, int fr, int fq) const {
;     ...
;             for (int m = 0; m < 4; ++m) { const bf16_t* rowp = XB + (size_t)(row0 + ai * HALF + m * 16) * ldc + col0;
; #pragma unroll
;                 for (int bj = 0; bj < 2; ++bj) res[m][bj] = *(const u32x4*)(rowp + bj * HALF); }
;             asm volatile("" ::: "memory");
; #pragma unroll
;             for (int m = 0; m < 4; ++m) { const int row = row0 + ai * HALF + m * 16; const size_t off = (size_t)row * ldc + col0;
;                 float rs = 1.0f; if (KS) rs = 1.0f / sqrtf(ss_get(ssb + row) * (1.0f / 1024.f) + 1e-6f);
;                 float sq = 0.f;
; #pragma unroll
;                 for (int bj = 0; bj < 2; ++bj) { const u32x4 r = res[m][bj];
;                     const f32x4 x0 = (f32x4){__uint_as_float(r.x << 16), __uint_as_float(r.x & 0xffff0000u), __uint_as_float(r.y << 16), __uint_as_float(r.y & 0xffff0000u)};
;                     const f32x4 x1 = (f32x4){__uint_as_float(r.z << 16), __uint_as_float(r.z & 0xffff0000u), __uint_as_float(r.w << 16), __uint_as_float(r.w & 0xffff0000u)};
;                     const f32x4 v0 = x0 + acc[ai][bj][m][0] * rs, v1 = x1 + acc[ai][bj][m][1] * rs;
;                     if (OUT) { *(f32x4*)(OUT + off + bj * HALF) = v0; *(f32x4*)(OUT + off + bj * HALF + 4) = v1; }
;                     else { sq += ((v0[0] * v0[0] + v0[1] * v0[1]) + (v0[2] * v0[2] + v0[3] * v0[3])) + ((v1[0] * v1[0] + v1[1] * v1[1]) + (v1[2] * v1[2] + v1[3] * v1[3]));
;                         u32x4 w; w.x = pkbf(v0[0], v0[1]); w.y = pkbf(v0[2], v0[3]); w.z = pkbf(v1[0], v1[1]); w.w = pkbf(v1[2], v1[3]); *(u32x4*)(XB + off + bj * HALF) = w; } }
;                 if (!OUT) { sq += __shfl_xor(sq, 16); sq += __shfl_xor(sq, 32); if (fq == 0) ss_add(ssq_out + row, sq); } }
.LBB0_931:
	v_lshl_or_b32 v0, s60, 8, v194
	v_mov_b32_e32 v182, v193
	v_ashrrev_i32_e32 v1, 31, v0
	v_lshlrev_b64 v[212:213], 1, v[0:1]
	v_ashrrev_i32_e32 v183, 31, v182
	v_lshl_add_u64 v[184:185], s[64:65], 0, v[212:213]
	v_lshlrev_b64 v[214:215], 12, v[182:183]
	v_add_u32_e32 v190, 16, v182
	v_lshl_add_u64 v[132:133], v[184:185], 0, v[214:215]
	v_ashrrev_i32_e32 v191, 31, v190
	global_load_dwordx4 v[196:199], v[132:133], off
	global_load_dwordx4 v[200:203], v[132:133], off offset:256
	v_lshlrev_b64 v[132:133], 12, v[190:191]
	v_add_u32_e32 v188, 32, v182
	v_lshl_add_u64 v[132:133], v[184:185], 0, v[132:133]
	v_ashrrev_i32_e32 v189, 31, v188
	global_load_dwordx4 v[152:155], v[132:133], off
	global_load_dwordx4 v[148:151], v[132:133], off offset:256
	v_lshlrev_b64 v[132:133], 12, v[188:189]
	v_add_u32_e32 v186, 48, v182
	v_lshl_add_u64 v[132:133], v[184:185], 0, v[132:133]
	v_ashrrev_i32_e32 v187, 31, v186
	global_load_dwordx4 v[144:147], v[132:133], off
	global_load_dwordx4 v[140:143], v[132:133], off offset:256
	v_lshlrev_b64 v[132:133], 12, v[186:187]
	v_lshl_add_u64 v[132:133], v[184:185], 0, v[132:133]
	global_load_dwordx4 v[136:139], v[132:133], off
	s_nop 0
	global_load_dwordx4 v[132:135], v[132:133], off offset:256
	v_lshl_add_u64 v[180:181], v[182:183], 3, s[8:9]
	s_flbit_i32_b32 s2, 0
	v_mov_b32_e32 v219, v2
	s_min_u32 s43, s2, 32
	s_sub_i32 s46, 32, s43
	s_waitcnt vmcnt(0)
	v_and_b32_e32 v221, 0xffff0000, v198
	v_mov_b32_e32 v216, v240
	s_nop 0
	s_nop 0
	s_nop 0
	s_nop 1
	s_nop 1
	s_nop 0
	v_lshlrev_b32_e32 v218, 16, v196
	v_and_b32_e32 v219, 0xffff0000, v196
	v_lshlrev_b32_e32 v196, 16, v197
	v_and_b32_e32 v197, 0xffff0000, v197
	v_lshlrev_b32_e32 v220, 16, v198
	v_lshlrev_b32_e32 v198, 16, v199
	v_and_b32_e32 v199, 0xffff0000, v199
	v_pk_fma_f32 v[130:131], v[130:131], v[216:217], v[196:197] op_sel_hi:[1,0,1]
	v_pk_fma_f32 v[128:129], v[128:129], v[216:217], v[218:219] op_sel_hi:[1,0,1]
	v_pk_fma_f32 v[196:197], v[126:127], v[216:217], v[198:199] op_sel_hi:[1,0,1]
	v_pk_fma_f32 v[126:127], v[124:125], v[216:217], v[220:221] op_sel_hi:[1,0,1]
	v_mul_f32_e32 v3, v129, v129
	v_mul_f32_e32 v124, v131, v131
	v_fmac_f32_e32 v3, v128, v128
	v_fmac_f32_e32 v124, v130, v130
	v_add_f32_e32 v3, v3, v124
	v_mul_f32_e32 v124, v127, v127
	v_mul_f32_e32 v125, v197, v197
	v_fmac_f32_e32 v124, v126, v126
	v_fmac_f32_e32 v125, v196, v196
	v_add_f32_e32 v124, v124, v125
	v_add_f32_e32 v3, v3, v124
	v_cvt_pk_bf16_f32 v124, v128, v129
	v_lshl_add_u64 v[128:129], s[64:65], 0, v[214:215]
	v_cvt_pk_bf16_f32 v125, v130, v131
	v_cvt_pk_bf16_f32 v126, v126, v127
	v_cvt_pk_bf16_f32 v127, v196, v197
	v_lshl_add_u64 v[128:129], v[128:129], 0, v[212:213]
	global_store_dwordx4 v[128:129], v[124:127], off
	v_lshlrev_b32_e32 v130, 16, v202
	v_and_b32_e32 v131, 0xffff0000, v202
	v_lshlrev_b32_e32 v124, 16, v200
	v_and_b32_e32 v125, 0xffff0000, v200
	v_lshlrev_b32_e32 v126, 16, v201
	v_and_b32_e32 v127, 0xffff0000, v201
	v_pk_fma_f32 v[122:123], v[122:123], v[216:217], v[126:127] op_sel_hi:[1,0,1]
	v_pk_fma_f32 v[120:121], v[120:121], v[216:217], v[124:125] op_sel_hi:[1,0,1]
	v_lshlrev_b32_e32 v196, 16, v203
	v_and_b32_e32 v197, 0xffff0000, v203
	v_pk_fma_f32 v[126:127], v[116:117], v[216:217], v[130:131] op_sel_hi:[1,0,1]
	v_mul_f32_e32 v116, v121, v121
	v_mul_f32_e32 v117, v123, v123
	v_pk_fma_f32 v[124:125], v[118:119], v[216:217], v[196:197] op_sel_hi:[1,0,1]
	v_fmac_f32_e32 v116, v120, v120
	v_fmac_f32_e32 v117, v122, v122
	v_add_f32_e32 v116, v116, v117
	v_mul_f32_e32 v117, v127, v127
	v_mul_f32_e32 v118, v125, v125
	v_fmac_f32_e32 v117, v126, v126
	v_fmac_f32_e32 v118, v124, v124
	v_add_f32_e32 v117, v117, v118
	v_add_f32_e32 v116, v116, v117
	v_and_b32_e32 v117, 64, v208
	v_add_f32_e32 v116, v3, v116
	v_xor_b32_e32 v3, 16, v208
	v_add_u32_e32 v117, 64, v117
	v_cmp_lt_i32_e32 vcc, v3, v117
	v_cvt_pk_bf16_f32 v118, v120, v121
	v_cvt_pk_bf16_f32 v119, v122, v123
	v_cndmask_b32_e32 v3, v208, v3, vcc
	v_cvt_pk_bf16_f32 v120, v126, v127
	v_cvt_pk_bf16_f32 v121, v124, v125
	v_lshlrev_b32_e32 v3, 2, v3
	global_store_dwordx4 v[128:129], v[118:121], off offset:256
	ds_bpermute_b32 v118, v3, v116
	s_waitcnt lgkmcnt(0)
	v_add_f32_e32 v116, v116, v118
	v_xor_b32_e32 v118, 32, v208
	v_cmp_lt_i32_e32 vcc, v118, v117
	s_nop 1
	v_cndmask_b32_e32 v117, v208, v118, vcc
	v_lshlrev_b32_e32 v117, 2, v117
	ds_bpermute_b32 v118, v117, v116
	s_and_saveexec_b64 s[2:3], s[40:41]
	s_cbranch_execz .LBB0_933
	s_waitcnt lgkmcnt(0)
	v_add_f32_e32 v116, v116, v118
	v_floor_f32_e32 v118, v116
	v_sub_f32_e32 v116, v116, v118
	v_mul_f32_e32 v116, 0x4f800000, v116
	v_cvt_u32_f32_e32 v119, v118
	v_cvt_u32_f32_e32 v118, v116
	v_lshl_add_u64 v[120:121], v[182:183], 3, s[4:5]
	global_atomic_add_x2 v[120:121], v[118:119], off
; __device__ __forceinline__ void ss_add(ss_t* p, float sq) { const float fl = floorf(sq); const unsigned hi = (unsigned)fl, lo = (unsigned)((sq - fl) * 4294967296.0f); atomicAdd(p, ((ss_t)hi << 32) | (ss_t)lo); }
; __device__ __forceinline__ float ss_get(const ss_t* p) { const ss_t v = *p; return (float)(unsigned)(v >> 32) + (float)(unsigned)v * 2.3283064365386963e-10f; }
;     __device__ __forceinline__ void operator()(const f32x4 (&acc)[2][2][4][2], const Unit& u, int wr, int wc, int fr, int fq) const {
;     ...
;             for (int m = 0; m < 4; ++m) { const bf16_t* rowp = XB + (size_t)(row0 + ai * HALF + m * 16) * ldc + col0;
; #pragma unroll
;                 for (int bj = 0; bj < 2; ++bj) res[m][bj] = *(const u32x4*)(rowp + bj * HALF); }
;             asm volatile("" ::: "memory");
; #pragma unroll
;             for (int m = 0; m < 4; ++m) { const int row = row0 + ai * HALF + m * 16; const size_t off = (size_t)row * ldc + col0;
;                 float rs = 1.0f; if (KS) rs = 1.0f / sqrtf(ss_get(ssb + row) * (1.0f / 1024.f) + 1e-6f);
;                 float sq = 0.f;
; #pragma unroll
;                 for (int bj = 0; bj < 2; ++bj) { const u32x4 r = res[m][bj];
;                     const f32x4 x0 = (f32x4){__uint_as_float(r.x << 16), __uint_as_float(r.x & 0xffff0000u), __uint_as_float(r.y << 16), __uint_as_float(r.y & 0xffff0000u)};
;                     const f32x4 x1 = (f32x4){__uint_as_float(r.z << 16), __uint_as_float(r.z & 0xffff0000u), __uint_as_float(r.w << 16), __uint_as_float(r.w & 0xffff0000u)};
;                     const f32x4 v0 = x0 + acc[ai][bj][m][0] * rs, v1 = x1 + acc[ai][bj][m][1] * rs;
;                     if (OUT) { *(f32x4*)(OUT + off + bj * HALF) = v0; *(f32x4*)(OUT + off + bj * HALF + 4) = v1; }
;                     else { sq += ((v0[0] * v0[0] + v0[1] * v0[1]) + (v0[2] * v0[2] + v0[3] * v0[3])) + ((v1[0] * v1[0] + v1[1] * v1[1]) + (v1[2] * v1[2] + v1[3] * v1[3]));
;                         u32x4 w; w.x = pkbf(v0[0], v0[1]); w.y = pkbf(v0[2], v0[3]); w.z = pkbf(v1[0], v1[1]); w.w = pkbf(v1[2], v1[3]); *(u32x4*)(XB + off + bj * HALF) = w; } }
;                 if (!OUT) { sq += __shfl_xor(sq, 16); sq += __shfl_xor(sq, 32); if (fq == 0) ss_add(ssq_out + row, sq); } }
.LBB0_933:
	s_or_b64 exec, exec, s[2:3]
	s_nop 0
	v_mov_b32_e32 v123, v2
	v_lshlrev_b32_e32 v126, 16, v155
	v_and_b32_e32 v127, 0xffff0000, v155
	v_and_b32_e32 v125, 0xffff0000, v154
	s_waitcnt lgkmcnt(0)
	v_lshlrev_b64 v[118:119], 11, v[190:191]
	v_mov_b32_e32 v116, v241
	s_nop 0
	s_nop 0
	s_nop 0
	s_nop 1
	s_nop 1
	s_nop 0
	v_lshlrev_b32_e32 v120, 16, v152
	v_and_b32_e32 v121, 0xffff0000, v152
	v_lshlrev_b32_e32 v122, 16, v153
	v_and_b32_e32 v123, 0xffff0000, v153
	v_pk_fma_f32 v[114:115], v[114:115], v[116:117], v[122:123] op_sel_hi:[1,0,1]
	v_pk_fma_f32 v[112:113], v[112:113], v[116:117], v[120:121] op_sel_hi:[1,0,1]
	v_lshlrev_b32_e32 v124, 16, v154
	v_pk_fma_f32 v[120:121], v[110:111], v[116:117], v[126:127] op_sel_hi:[1,0,1]
	v_mul_f32_e32 v110, v113, v113
	v_mul_f32_e32 v111, v115, v115
	v_pk_fma_f32 v[108:109], v[108:109], v[116:117], v[124:125] op_sel_hi:[1,0,1]
	v_fmac_f32_e32 v110, v112, v112
	v_fmac_f32_e32 v111, v114, v114
	v_add_f32_e32 v110, v110, v111
	v_mul_f32_e32 v111, v109, v109
	v_mul_f32_e32 v122, v121, v121
	v_fmac_f32_e32 v111, v108, v108
	v_fmac_f32_e32 v122, v120, v120
	v_add_f32_e32 v111, v111, v122
	v_add_f32_e32 v122, v110, v111
	v_cvt_pk_bf16_f32 v110, v112, v113
	v_cvt_pk_bf16_f32 v112, v108, v109
	v_lshl_add_u64 v[108:109], v[118:119], 1, s[64:65]
	v_cvt_pk_bf16_f32 v111, v114, v115
	v_cvt_pk_bf16_f32 v113, v120, v121
	v_lshl_add_u64 v[108:109], v[0:1], 1, v[108:109]
	global_store_dwordx4 v[108:109], v[110:113], off
	v_lshlrev_b32_e32 v114, 16, v150
	v_and_b32_e32 v115, 0xffff0000, v150
	v_lshlrev_b32_e32 v110, 16, v148
	v_and_b32_e32 v111, 0xffff0000, v148
	v_lshlrev_b32_e32 v112, 16, v149
	v_and_b32_e32 v113, 0xffff0000, v149
	v_lshlrev_b32_e32 v118, 16, v151
	v_and_b32_e32 v119, 0xffff0000, v151
	v_pk_fma_f32 v[106:107], v[106:107], v[116:117], v[112:113] op_sel_hi:[1,0,1]
	v_pk_fma_f32 v[104:105], v[104:105], v[116:117], v[110:111] op_sel_hi:[1,0,1]
	v_pk_fma_f32 v[110:111], v[102:103], v[116:117], v[118:119] op_sel_hi:[1,0,1]
	v_pk_fma_f32 v[102:103], v[100:101], v[116:117], v[114:115] op_sel_hi:[1,0,1]
	v_mul_f32_e32 v100, v105, v105
	v_mul_f32_e32 v101, v107, v107
	v_fmac_f32_e32 v100, v104, v104
	v_fmac_f32_e32 v101, v106, v106
	v_add_f32_e32 v100, v100, v101
	v_mul_f32_e32 v101, v103, v103
	v_mul_f32_e32 v112, v111, v111
	v_fmac_f32_e32 v101, v102, v102
	v_fmac_f32_e32 v112, v110, v110
	v_add_f32_e32 v101, v101, v112
	v_add_f32_e32 v100, v100, v101
	v_add_f32_e32 v112, v122, v100
	v_cvt_pk_bf16_f32 v100, v104, v105
	v_cvt_pk_bf16_f32 v101, v106, v107
	v_cvt_pk_bf16_f32 v102, v102, v103
	v_cvt_pk_bf16_f32 v103, v110, v111
	global_store_dwordx4 v[108:109], v[100:103], off offset:256
	ds_bpermute_b32 v100, v3, v112
	s_waitcnt lgkmcnt(0)
	v_add_f32_e32 v100, v112, v100
	ds_bpermute_b32 v101, v117, v100
	s_and_saveexec_b64 s[2:3], s[40:41]
	s_cbranch_execz .LBB0_935
	s_waitcnt lgkmcnt(0)
	v_add_f32_e32 v102, v100, v101
	v_floor_f32_e32 v104, v102
	v_sub_f32_e32 v102, v102, v104
	v_mul_f32_e32 v102, 0x4f800000, v102
	v_cvt_u32_f32_e32 v103, v104
	v_cvt_u32_f32_e32 v102, v102
	v_lshl_add_u64 v[100:101], v[190:191], 3, s[4:5]
	global_atomic_add_x2 v[100:101], v[102:103], off
.LBB0_935:
	s_or_b64 exec, exec, s[2:3]
	s_waitcnt lgkmcnt(0)
	s_nop 0
	v_mov_b32_e32 v105, v2
	v_lshlrev_b32_e32 v110, 16, v147
	v_and_b32_e32 v111, 0xffff0000, v147
	v_lshlrev_b32_e32 v108, 16, v146
	v_and_b32_e32 v109, 0xffff0000, v146
	v_lshlrev_b64 v[102:103], 11, v[188:189]
	v_mov_b32_e32 v100, v242
	s_nop 0
	s_nop 0
	s_nop 0
	s_nop 1
	s_nop 1
	s_nop 0
	v_lshlrev_b32_e32 v104, 16, v144
	v_and_b32_e32 v105, 0xffff0000, v144
	v_lshlrev_b32_e32 v106, 16, v145
	v_and_b32_e32 v107, 0xffff0000, v145
	v_pk_fma_f32 v[98:99], v[98:99], v[100:101], v[106:107] op_sel_hi:[1,0,1]
	v_pk_fma_f32 v[96:97], v[96:97], v[100:101], v[104:105] op_sel_hi:[1,0,1]
	v_pk_fma_f32 v[104:105], v[94:95], v[100:101], v[110:111] op_sel_hi:[1,0,1]
	v_mul_f32_e32 v94, v97, v97
	v_mul_f32_e32 v95, v99, v99
	v_pk_fma_f32 v[92:93], v[92:93], v[100:101], v[108:109] op_sel_hi:[1,0,1]
	v_fmac_f32_e32 v94, v96, v96
	v_fmac_f32_e32 v95, v98, v98
	v_add_f32_e32 v94, v94, v95
	v_mul_f32_e32 v95, v93, v93
	v_mul_f32_e32 v101, v105, v105
	v_fmac_f32_e32 v95, v92, v92
	v_fmac_f32_e32 v101, v104, v104
	v_add_f32_e32 v95, v95, v101
	v_add_f32_e32 v101, v94, v95
	v_cvt_pk_bf16_f32 v94, v96, v97
	v_cvt_pk_bf16_f32 v96, v92, v93
	v_lshl_add_u64 v[92:93], v[102:103], 1, s[64:65]
	v_cvt_pk_bf16_f32 v95, v98, v99
	v_cvt_pk_bf16_f32 v97, v104, v105
	v_lshl_add_u64 v[92:93], v[0:1], 1, v[92:93]
	global_store_dwordx4 v[92:93], v[94:97], off
	v_lshlrev_b32_e32 v98, 16, v142
	v_and_b32_e32 v99, 0xffff0000, v142
	v_lshlrev_b32_e32 v94, 16, v140
	v_and_b32_e32 v95, 0xffff0000, v140
	v_lshlrev_b32_e32 v96, 16, v141
	v_and_b32_e32 v97, 0xffff0000, v141
	v_lshlrev_b32_e32 v102, 16, v143
	v_and_b32_e32 v103, 0xffff0000, v143
	v_pk_fma_f32 v[90:91], v[90:91], v[100:101], v[96:97] op_sel_hi:[1,0,1]
	v_pk_fma_f32 v[88:89], v[88:89], v[100:101], v[94:95] op_sel_hi:[1,0,1]
	v_pk_fma_f32 v[94:95], v[86:87], v[100:101], v[102:103] op_sel_hi:[1,0,1]
	v_pk_fma_f32 v[86:87], v[84:85], v[100:101], v[98:99] op_sel_hi:[1,0,1]
	v_mul_f32_e32 v84, v89, v89
	v_mul_f32_e32 v85, v91, v91
	v_fmac_f32_e32 v84, v88, v88
	v_fmac_f32_e32 v85, v90, v90
	v_add_f32_e32 v84, v84, v85
	v_mul_f32_e32 v85, v87, v87
	v_mul_f32_e32 v96, v95, v95
	v_fmac_f32_e32 v85, v86, v86
	v_fmac_f32_e32 v96, v94, v94
	v_add_f32_e32 v85, v85, v96
	v_add_f32_e32 v84, v84, v85
	v_add_f32_e32 v96, v101, v84
	v_cvt_pk_bf16_f32 v84, v88, v89
	v_cvt_pk_bf16_f32 v85, v90, v91
	v_cvt_pk_bf16_f32 v86, v86, v87
	v_cvt_pk_bf16_f32 v87, v94, v95
	global_store_dwordx4 v[92:93], v[84:87], off offset:256
	ds_bpermute_b32 v84, v3, v96
	s_waitcnt lgkmcnt(0)
	v_add_f32_e32 v84, v96, v84
	ds_bpermute_b32 v85, v117, v84
	s_and_saveexec_b64 s[2:3], s[40:41]
	s_cbranch_execz .LBB0_937
	s_waitcnt lgkmcnt(0)
	v_add_f32_e32 v86, v84, v85
	v_floor_f32_e32 v88, v86
	v_sub_f32_e32 v86, v86, v88
	v_mul_f32_e32 v86, 0x4f800000, v86
	v_cvt_u32_f32_e32 v87, v88
	v_cvt_u32_f32_e32 v86, v86
	v_lshl_add_u64 v[84:85], v[188:189], 3, s[4:5]
	global_atomic_add_x2 v[84:85], v[86:87], off
; __device__ __forceinline__ void ss_add(ss_t* p, float sq) { const float fl = floorf(sq); const unsigned hi = (unsigned)fl, lo = (unsigned)((sq - fl) * 4294967296.0f); atomicAdd(p, ((ss_t)hi << 32) | (ss_t)lo); }
; __device__ __forceinline__ float ss_get(const ss_t* p) { const ss_t v = *p; return (float)(unsigned)(v >> 32) + (float)(unsigned)v * 2.3283064365386963e-10f; }
;     __device__ __forceinline__ void operator()(const f32x4 (&acc)[2][2][4][2], const Unit& u, int wr, int wc, int fr, int fq) const {
;     ...
;             for (int m = 0; m < 4; ++m) { const bf16_t* rowp = XB + (size_t)(row0 + ai * HALF + m * 16) * ldc + col0;
; #pragma unroll
;                 for (int bj = 0; bj < 2; ++bj) res[m][bj] = *(const u32x4*)(rowp + bj * HALF); }
;             asm volatile("" ::: "memory");
; #pragma unroll
;             for (int m = 0; m < 4; ++m) { const int row = row0 + ai * HALF + m * 16; const size_t off = (size_t)row * ldc + col0;
;                 float rs = 1.0f; if (KS) rs = 1.0f / sqrtf(ss_get(ssb + row) * (1.0f / 1024.f) + 1e-6f);
;                 float sq = 0.f;
; #pragma unroll
;                 for (int bj = 0; bj < 2; ++bj) { const u32x4 r = res[m][bj];
;                     const f32x4 x0 = (f32x4){__uint_as_float(r.x << 16), __uint_as_float(r.x & 0xffff0000u), __uint_as_float(r.y << 16), __uint_as_float(r.y & 0xffff0000u)};
;                     const f32x4 x1 = (f32x4){__uint_as_float(r.z << 16), __uint_as_float(r.z & 0xffff0000u), __uint_as_float(r.w << 16), __uint_as_float(r.w & 0xffff0000u)};
;                     const f32x4 v0 = x0 + acc[ai][bj][m][0] * rs, v1 = x1 + acc[ai][bj][m][1] * rs;
;                     if (OUT) { *(f32x4*)(OUT + off + bj * HALF) = v0; *(f32x4*)(OUT + off + bj * HALF + 4) = v1; }
;                     else { sq += ((v0[0] * v0[0] + v0[1] * v0[1]) + (v0[2] * v0[2] + v0[3] * v0[3])) + ((v1[0] * v1[0] + v1[1] * v1[1]) + (v1[2] * v1[2] + v1[3] * v1[3]));
;                         u32x4 w; w.x = pkbf(v0[0], v0[1]); w.y = pkbf(v0[2], v0[3]); w.z = pkbf(v1[0], v1[1]); w.w = pkbf(v1[2], v1[3]); *(u32x4*)(XB + off + bj * HALF) = w; } }
;                 if (!OUT) { sq += __shfl_xor(sq, 16); sq += __shfl_xor(sq, 32); if (fq == 0) ss_add(ssq_out + row, sq); } }
.LBB0_937:
	s_or_b64 exec, exec, s[2:3]
	s_waitcnt lgkmcnt(0)
	s_nop 0
	v_mov_b32_e32 v89, v2
	v_lshlrev_b32_e32 v94, 16, v139
	v_and_b32_e32 v95, 0xffff0000, v139
	v_lshlrev_b32_e32 v92, 16, v138
	v_and_b32_e32 v93, 0xffff0000, v138
	v_lshlrev_b64 v[86:87], 11, v[186:187]
	v_mov_b32_e32 v84, v243
	s_nop 0
	s_nop 0
	s_nop 0
	s_nop 1
	s_nop 1
	s_nop 0
	v_lshlrev_b32_e32 v88, 16, v136
	v_and_b32_e32 v89, 0xffff0000, v136
	v_lshlrev_b32_e32 v90, 16, v137
	v_and_b32_e32 v91, 0xffff0000, v137
	v_pk_fma_f32 v[82:83], v[82:83], v[84:85], v[90:91] op_sel_hi:[1,0,1]
	v_pk_fma_f32 v[80:81], v[80:81], v[84:85], v[88:89] op_sel_hi:[1,0,1]
	v_pk_fma_f32 v[88:89], v[78:79], v[84:85], v[94:95] op_sel_hi:[1,0,1]
	v_mul_f32_e32 v78, v81, v81
	v_mul_f32_e32 v79, v83, v83
	v_pk_fma_f32 v[76:77], v[76:77], v[84:85], v[92:93] op_sel_hi:[1,0,1]
	v_fmac_f32_e32 v78, v80, v80
	v_fmac_f32_e32 v79, v82, v82
	v_add_f32_e32 v78, v78, v79
	v_mul_f32_e32 v79, v77, v77
	v_mul_f32_e32 v85, v89, v89
	v_fmac_f32_e32 v79, v76, v76
	v_fmac_f32_e32 v85, v88, v88
	v_add_f32_e32 v79, v79, v85
	v_add_f32_e32 v85, v78, v79
	v_cvt_pk_bf16_f32 v78, v80, v81
	v_cvt_pk_bf16_f32 v80, v76, v77
	v_lshl_add_u64 v[76:77], v[86:87], 1, s[64:65]
	v_cvt_pk_bf16_f32 v79, v82, v83
	v_cvt_pk_bf16_f32 v81, v88, v89
	v_lshl_add_u64 v[76:77], v[0:1], 1, v[76:77]
	global_store_dwordx4 v[76:77], v[78:81], off
	v_lshlrev_b32_e32 v82, 16, v134
	v_and_b32_e32 v83, 0xffff0000, v134
	v_lshlrev_b32_e32 v78, 16, v132
	v_and_b32_e32 v79, 0xffff0000, v132
	v_lshlrev_b32_e32 v80, 16, v133
	v_and_b32_e32 v81, 0xffff0000, v133
	v_lshlrev_b32_e32 v86, 16, v135
	v_and_b32_e32 v87, 0xffff0000, v135
	v_pk_fma_f32 v[74:75], v[74:75], v[84:85], v[80:81] op_sel_hi:[1,0,1]
	v_pk_fma_f32 v[72:73], v[72:73], v[84:85], v[78:79] op_sel_hi:[1,0,1]
	v_pk_fma_f32 v[78:79], v[70:71], v[84:85], v[86:87] op_sel_hi:[1,0,1]
	v_pk_fma_f32 v[70:71], v[68:69], v[84:85], v[82:83] op_sel_hi:[1,0,1]
	v_mul_f32_e32 v68, v73, v73
	v_mul_f32_e32 v69, v75, v75
	v_fmac_f32_e32 v68, v72, v72
	v_fmac_f32_e32 v69, v74, v74
	v_add_f32_e32 v68, v68, v69
	v_mul_f32_e32 v69, v71, v71
	v_mul_f32_e32 v80, v79, v79
	v_fmac_f32_e32 v69, v70, v70
	v_fmac_f32_e32 v80, v78, v78
	v_add_f32_e32 v69, v69, v80
	v_add_f32_e32 v68, v68, v69
	v_add_f32_e32 v80, v85, v68
	v_cvt_pk_bf16_f32 v68, v72, v73
	v_cvt_pk_bf16_f32 v69, v74, v75
	v_cvt_pk_bf16_f32 v70, v70, v71
	v_cvt_pk_bf16_f32 v71, v78, v79
	global_store_dwordx4 v[76:77], v[68:71], off offset:256
	ds_bpermute_b32 v68, v3, v80
	s_waitcnt lgkmcnt(0)
	v_add_f32_e32 v68, v80, v68
	ds_bpermute_b32 v69, v117, v68
	s_and_saveexec_b64 s[2:3], s[40:41]
	s_cbranch_execz .LBB0_939
	s_waitcnt lgkmcnt(0)
	v_add_f32_e32 v70, v68, v69
	v_floor_f32_e32 v72, v70
	v_sub_f32_e32 v70, v70, v72
	v_mul_f32_e32 v70, 0x4f800000, v70
	v_cvt_u32_f32_e32 v71, v72
	v_cvt_u32_f32_e32 v70, v70
	v_lshl_add_u64 v[68:69], v[186:187], 3, s[4:5]
	global_atomic_add_x2 v[68:69], v[70:71], off
.LBB0_939:
	s_or_b64 exec, exec, s[2:3]
	v_add_u32_e32 v102, 0x80, v182
	v_ashrrev_i32_e32 v103, 31, v102
	v_lshlrev_b64 v[110:111], 12, v[102:103]
	v_add_u32_e32 v100, 0x90, v182
	s_waitcnt lgkmcnt(0)
	v_lshl_add_u64 v[68:69], v[184:185], 0, v[110:111]
	v_ashrrev_i32_e32 v101, 31, v100
	global_load_dwordx4 v[106:109], v[68:69], off
	global_load_dwordx4 v[92:95], v[68:69], off offset:256
	v_lshlrev_b64 v[68:69], 12, v[100:101]
	v_add_u32_e32 v98, 0xa0, v182
	v_lshl_add_u64 v[68:69], v[184:185], 0, v[68:69]
	v_ashrrev_i32_e32 v99, 31, v98
	global_load_dwordx4 v[88:91], v[68:69], off
	global_load_dwordx4 v[84:87], v[68:69], off offset:256
	v_lshlrev_b64 v[68:69], 12, v[98:99]
	v_add_u32_e32 v96, 0xb0, v182
	v_lshl_add_u64 v[68:69], v[184:185], 0, v[68:69]
	v_ashrrev_i32_e32 v97, 31, v96
	global_load_dwordx4 v[80:83], v[68:69], off
	global_load_dwordx4 v[76:79], v[68:69], off offset:256
	v_lshlrev_b64 v[68:69], 12, v[96:97]
	v_lshl_add_u64 v[68:69], v[184:185], 0, v[68:69]
	global_load_dwordx4 v[72:75], v[68:69], off
	s_nop 0
	global_load_dwordx4 v[68:71], v[68:69], off offset:256
	s_nop 0
	v_mov_b32_e32 v113, v2
	s_waitcnt vmcnt(0)
	v_mov_b32_e32 v104, v244
	s_nop 0
	s_nop 0
	s_nop 0
	s_nop 1
	s_nop 1
	s_nop 0
	v_lshlrev_b32_e32 v112, 16, v106
	v_and_b32_e32 v113, 0xffff0000, v106
	v_lshlrev_b32_e32 v106, 16, v107
	v_and_b32_e32 v107, 0xffff0000, v107
	v_lshlrev_b32_e32 v114, 16, v108
	v_and_b32_e32 v115, 0xffff0000, v108
	v_lshlrev_b32_e32 v108, 16, v109
	v_and_b32_e32 v109, 0xffff0000, v109
	v_pk_fma_f32 v[66:67], v[66:67], v[104:105], v[106:107] op_sel_hi:[1,0,1]
	v_pk_fma_f32 v[64:65], v[64:65], v[104:105], v[112:113] op_sel_hi:[1,0,1]
	v_pk_fma_f32 v[106:107], v[62:63], v[104:105], v[108:109] op_sel_hi:[1,0,1]
	v_mul_f32_e32 v62, v65, v65
	v_mul_f32_e32 v63, v67, v67
	v_pk_fma_f32 v[60:61], v[60:61], v[104:105], v[114:115] op_sel_hi:[1,0,1]
	v_fmac_f32_e32 v62, v64, v64
	v_fmac_f32_e32 v63, v66, v66
	v_add_f32_e32 v62, v62, v63
	v_mul_f32_e32 v63, v61, v61
	v_mul_f32_e32 v105, v107, v107
	v_fmac_f32_e32 v63, v60, v60
	v_fmac_f32_e32 v105, v106, v106
	v_add_f32_e32 v63, v63, v105
	v_add_f32_e32 v105, v62, v63
	v_cvt_pk_bf16_f32 v62, v64, v65
	v_cvt_pk_bf16_f32 v64, v60, v61
	v_lshl_add_u64 v[60:61], s[64:65], 0, v[110:111]
	v_cvt_pk_bf16_f32 v63, v66, v67
	v_cvt_pk_bf16_f32 v65, v106, v107
	v_lshl_add_u64 v[60:61], v[0:1], 1, v[60:61]
	global_store_dwordx4 v[60:61], v[62:65], off
	v_lshlrev_b32_e32 v66, 16, v94
	v_and_b32_e32 v67, 0xffff0000, v94
	v_lshlrev_b32_e32 v62, 16, v92
	v_and_b32_e32 v63, 0xffff0000, v92
	v_lshlrev_b32_e32 v64, 16, v93
	v_and_b32_e32 v65, 0xffff0000, v93
	v_lshlrev_b32_e32 v92, 16, v95
	v_and_b32_e32 v93, 0xffff0000, v95
	v_pk_fma_f32 v[58:59], v[58:59], v[104:105], v[64:65] op_sel_hi:[1,0,1]
	v_pk_fma_f32 v[56:57], v[56:57], v[104:105], v[62:63] op_sel_hi:[1,0,1]
	v_pk_fma_f32 v[62:63], v[54:55], v[104:105], v[92:93] op_sel_hi:[1,0,1]
	v_pk_fma_f32 v[54:55], v[52:53], v[104:105], v[66:67] op_sel_hi:[1,0,1]
	v_mul_f32_e32 v52, v57, v57
	v_mul_f32_e32 v53, v59, v59
	v_fmac_f32_e32 v52, v56, v56
	v_fmac_f32_e32 v53, v58, v58
	v_add_f32_e32 v52, v52, v53
	v_mul_f32_e32 v53, v55, v55
	v_mul_f32_e32 v64, v63, v63
	v_fmac_f32_e32 v53, v54, v54
	v_fmac_f32_e32 v64, v62, v62
	v_add_f32_e32 v53, v53, v64
	v_add_f32_e32 v52, v52, v53
	v_add_f32_e32 v64, v105, v52
	v_cvt_pk_bf16_f32 v52, v56, v57
	v_cvt_pk_bf16_f32 v53, v58, v59
	v_cvt_pk_bf16_f32 v54, v54, v55
	v_cvt_pk_bf16_f32 v55, v62, v63
	global_store_dwordx4 v[60:61], v[52:55], off offset:256
	ds_bpermute_b32 v52, v3, v64
	s_waitcnt lgkmcnt(0)
	v_add_f32_e32 v52, v64, v52
	ds_bpermute_b32 v53, v117, v52
	s_and_saveexec_b64 s[2:3], s[40:41]
	s_cbranch_execz .LBB0_941
	s_waitcnt lgkmcnt(0)
	v_add_f32_e32 v54, v52, v53
	v_floor_f32_e32 v56, v54
	v_sub_f32_e32 v54, v54, v56
	v_mul_f32_e32 v54, 0x4f800000, v54
	v_cvt_u32_f32_e32 v55, v56
	v_cvt_u32_f32_e32 v54, v54
	v_lshl_add_u64 v[52:53], v[102:103], 3, s[4:5]
	global_atomic_add_x2 v[52:53], v[54:55], off
; __device__ __forceinline__ void ss_add(ss_t* p, float sq) { const float fl = floorf(sq); const unsigned hi = (unsigned)fl, lo = (unsigned)((sq - fl) * 4294967296.0f); atomicAdd(p, ((ss_t)hi << 32) | (ss_t)lo); }
; __device__ __forceinline__ float ss_get(const ss_t* p) { const ss_t v = *p; return (float)(unsigned)(v >> 32) + (float)(unsigned)v * 2.3283064365386963e-10f; }
;     __device__ __forceinline__ void operator()(const f32x4 (&acc)[2][2][4][2], const Unit& u, int wr, int wc, int fr, int fq) const {
;     ...
;             for (int m = 0; m < 4; ++m) { const bf16_t* rowp = XB + (size_t)(row0 + ai * HALF + m * 16) * ldc + col0;
; #pragma unroll
;                 for (int bj = 0; bj < 2; ++bj) res[m][bj] = *(const u32x4*)(rowp + bj * HALF); }
;             asm volatile("" ::: "memory");
; #pragma unroll
;             for (int m = 0; m < 4; ++m) { const int row = row0 + ai * HALF + m * 16; const size_t off = (size_t)row * ldc + col0;
;                 float rs = 1.0f; if (KS) rs = 1.0f / sqrtf(ss_get(ssb + row) * (1.0f / 1024.f) + 1e-6f);
;                 float sq = 0.f;
; #pragma unroll
;                 for (int bj = 0; bj < 2; ++bj) { const u32x4 r = res[m][bj];
;                     const f32x4 x0 = (f32x4){__uint_as_float(r.x << 16), __uint_as_float(r.x & 0xffff0000u), __uint_as_float(r.y << 16), __uint_as_float(r.y & 0xffff0000u)};
;                     const f32x4 x1 = (f32x4){__uint_as_float(r.z << 16), __uint_as_float(r.z & 0xffff0000u), __uint_as_float(r.w << 16), __uint_as_float(r.w & 0xffff0000u)};
;                     const f32x4 v0 = x0 + acc[ai][bj][m][0] * rs, v1 = x1 + acc[ai][bj][m][1] * rs;
;                     if (OUT) { *(f32x4*)(OUT + off + bj * HALF) = v0; *(f32x4*)(OUT + off + bj * HALF + 4) = v1; }
;                     else { sq += ((v0[0] * v0[0] + v0[1] * v0[1]) + (v0[2] * v0[2] + v0[3] * v0[3])) + ((v1[0] * v1[0] + v1[1] * v1[1]) + (v1[2] * v1[2] + v1[3] * v1[3]));
;                         u32x4 w; w.x = pkbf(v0[0], v0[1]); w.y = pkbf(v0[2], v0[3]); w.z = pkbf(v1[0], v1[1]); w.w = pkbf(v1[2], v1[3]); *(u32x4*)(XB + off + bj * HALF) = w; } }
;                 if (!OUT) { sq += __shfl_xor(sq, 16); sq += __shfl_xor(sq, 32); if (fq == 0) ss_add(ssq_out + row, sq); } }
.LBB0_941:
	s_or_b64 exec, exec, s[2:3]
	s_waitcnt lgkmcnt(0)
	s_nop 0
	v_mov_b32_e32 v57, v2
	v_lshlrev_b32_e32 v62, 16, v91
	v_and_b32_e32 v63, 0xffff0000, v91
	v_lshlrev_b32_e32 v60, 16, v90
	v_and_b32_e32 v61, 0xffff0000, v90
	v_lshlrev_b64 v[54:55], 11, v[100:101]
	v_mov_b32_e32 v52, v245
	s_nop 0
	s_nop 0
	s_nop 0
	s_nop 1
	s_nop 1
	s_nop 0
	v_lshlrev_b32_e32 v56, 16, v88
	v_and_b32_e32 v57, 0xffff0000, v88
	v_lshlrev_b32_e32 v58, 16, v89
	v_and_b32_e32 v59, 0xffff0000, v89
	v_pk_fma_f32 v[50:51], v[50:51], v[52:53], v[58:59] op_sel_hi:[1,0,1]
	v_pk_fma_f32 v[48:49], v[48:49], v[52:53], v[56:57] op_sel_hi:[1,0,1]
	v_pk_fma_f32 v[56:57], v[46:47], v[52:53], v[62:63] op_sel_hi:[1,0,1]
	v_mul_f32_e32 v46, v49, v49
	v_mul_f32_e32 v47, v51, v51
	v_pk_fma_f32 v[44:45], v[44:45], v[52:53], v[60:61] op_sel_hi:[1,0,1]
	v_fmac_f32_e32 v46, v48, v48
	v_fmac_f32_e32 v47, v50, v50
	v_add_f32_e32 v46, v46, v47
	v_mul_f32_e32 v47, v45, v45
	v_mul_f32_e32 v53, v57, v57
	v_fmac_f32_e32 v47, v44, v44
	v_fmac_f32_e32 v53, v56, v56
	v_add_f32_e32 v47, v47, v53
	v_add_f32_e32 v53, v46, v47
	v_cvt_pk_bf16_f32 v46, v48, v49
	v_cvt_pk_bf16_f32 v48, v44, v45
	v_lshl_add_u64 v[44:45], v[54:55], 1, s[64:65]
	v_cvt_pk_bf16_f32 v47, v50, v51
	v_cvt_pk_bf16_f32 v49, v56, v57
	v_lshl_add_u64 v[44:45], v[0:1], 1, v[44:45]
	global_store_dwordx4 v[44:45], v[46:49], off
	v_lshlrev_b32_e32 v50, 16, v86
	v_and_b32_e32 v51, 0xffff0000, v86
	v_lshlrev_b32_e32 v46, 16, v84
	v_and_b32_e32 v47, 0xffff0000, v84
	v_lshlrev_b32_e32 v48, 16, v85
	v_and_b32_e32 v49, 0xffff0000, v85
	v_lshlrev_b32_e32 v54, 16, v87
	v_and_b32_e32 v55, 0xffff0000, v87
	v_pk_fma_f32 v[42:43], v[42:43], v[52:53], v[48:49] op_sel_hi:[1,0,1]
	v_pk_fma_f32 v[40:41], v[40:41], v[52:53], v[46:47] op_sel_hi:[1,0,1]
	v_pk_fma_f32 v[46:47], v[38:39], v[52:53], v[54:55] op_sel_hi:[1,0,1]
	v_pk_fma_f32 v[38:39], v[36:37], v[52:53], v[50:51] op_sel_hi:[1,0,1]
	v_mul_f32_e32 v36, v41, v41
	v_mul_f32_e32 v37, v43, v43
	v_fmac_f32_e32 v36, v40, v40
	v_fmac_f32_e32 v37, v42, v42
	v_add_f32_e32 v36, v36, v37
	v_mul_f32_e32 v37, v39, v39
	v_mul_f32_e32 v48, v47, v47
	v_fmac_f32_e32 v37, v38, v38
	v_fmac_f32_e32 v48, v46, v46
	v_add_f32_e32 v37, v37, v48
	v_add_f32_e32 v36, v36, v37
	v_add_f32_e32 v48, v53, v36
	v_cvt_pk_bf16_f32 v36, v40, v41
	v_cvt_pk_bf16_f32 v37, v42, v43
	v_cvt_pk_bf16_f32 v38, v38, v39
	v_cvt_pk_bf16_f32 v39, v46, v47
	global_store_dwordx4 v[44:45], v[36:39], off offset:256
	ds_bpermute_b32 v36, v3, v48
	s_waitcnt lgkmcnt(0)
	v_add_f32_e32 v36, v48, v36
	ds_bpermute_b32 v37, v117, v36
	s_and_saveexec_b64 s[2:3], s[40:41]
	s_cbranch_execz .LBB0_943
	s_waitcnt lgkmcnt(0)
	v_add_f32_e32 v38, v36, v37
	v_floor_f32_e32 v40, v38
	v_sub_f32_e32 v38, v38, v40
	v_mul_f32_e32 v38, 0x4f800000, v38
	v_cvt_u32_f32_e32 v39, v40
	v_cvt_u32_f32_e32 v38, v38
	v_lshl_add_u64 v[36:37], v[100:101], 3, s[4:5]
	global_atomic_add_x2 v[36:37], v[38:39], off
; __device__ __forceinline__ void ss_add(ss_t* p, float sq) { const float fl = floorf(sq); const unsigned hi = (unsigned)fl, lo = (unsigned)((sq - fl) * 4294967296.0f); atomicAdd(p, ((ss_t)hi << 32) | (ss_t)lo); }
; __device__ __forceinline__ float ss_get(const ss_t* p) { const ss_t v = *p; return (float)(unsigned)(v >> 32) + (float)(unsigned)v * 2.3283064365386963e-10f; }
;     __device__ __forceinline__ void operator()(const f32x4 (&acc)[2][2][4][2], const Unit& u, int wr, int wc, int fr, int fq) const {
;     ...
;             for (int m = 0; m < 4; ++m) { const bf16_t* rowp = XB + (size_t)(row0 + ai * HALF + m * 16) * ldc + col0;
; #pragma unroll
;                 for (int bj = 0; bj < 2; ++bj) res[m][bj] = *(const u32x4*)(rowp + bj * HALF); }
;             asm volatile("" ::: "memory");
; #pragma unroll
;             for (int m = 0; m < 4; ++m) { const int row = row0 + ai * HALF + m * 16; const size_t off = (size_t)row * ldc + col0;
;                 float rs = 1.0f; if (KS) rs = 1.0f / sqrtf(ss_get(ssb + row) * (1.0f / 1024.f) + 1e-6f);
;                 float sq = 0.f;
; #pragma unroll
;                 for (int bj = 0; bj < 2; ++bj) { const u32x4 r = res[m][bj];
;                     const f32x4 x0 = (f32x4){__uint_as_float(r.x << 16), __uint_as_float(r.x & 0xffff0000u), __uint_as_float(r.y << 16), __uint_as_float(r.y & 0xffff0000u)};
;                     const f32x4 x1 = (f32x4){__uint_as_float(r.z << 16), __uint_as_float(r.z & 0xffff0000u), __uint_as_float(r.w << 16), __uint_as_float(r.w & 0xffff0000u)};
;                     const f32x4 v0 = x0 + acc[ai][bj][m][0] * rs, v1 = x1 + acc[ai][bj][m][1] * rs;
;                     if (OUT) { *(f32x4*)(OUT + off + bj * HALF) = v0; *(f32x4*)(OUT + off + bj * HALF + 4) = v1; }
;                     else { sq += ((v0[0] * v0[0] + v0[1] * v0[1]) + (v0[2] * v0[2] + v0[3] * v0[3])) + ((v1[0] * v1[0] + v1[1] * v1[1]) + (v1[2] * v1[2] + v1[3] * v1[3]));
;                         u32x4 w; w.x = pkbf(v0[0], v0[1]); w.y = pkbf(v0[2], v0[3]); w.z = pkbf(v1[0], v1[1]); w.w = pkbf(v1[2], v1[3]); *(u32x4*)(XB + off + bj * HALF) = w; } }
;                 if (!OUT) { sq += __shfl_xor(sq, 16); sq += __shfl_xor(sq, 32); if (fq == 0) ss_add(ssq_out + row, sq); } }
.LBB0_943:
	s_or_b64 exec, exec, s[2:3]
	s_waitcnt lgkmcnt(0)
	s_nop 0
	v_mov_b32_e32 v41, v2
	v_lshlrev_b32_e32 v46, 16, v83
	v_and_b32_e32 v47, 0xffff0000, v83
	v_lshlrev_b32_e32 v44, 16, v82
	v_and_b32_e32 v45, 0xffff0000, v82
	v_lshlrev_b64 v[38:39], 11, v[98:99]
	v_mov_b32_e32 v36, v246
	s_nop 0
	s_nop 0
	s_nop 0
	s_nop 1
	s_nop 1
	s_nop 0
	v_lshlrev_b32_e32 v40, 16, v80
	v_and_b32_e32 v41, 0xffff0000, v80
	v_lshlrev_b32_e32 v42, 16, v81
	v_and_b32_e32 v43, 0xffff0000, v81
	v_pk_fma_f32 v[34:35], v[34:35], v[36:37], v[42:43] op_sel_hi:[1,0,1]
	v_pk_fma_f32 v[32:33], v[32:33], v[36:37], v[40:41] op_sel_hi:[1,0,1]
	v_pk_fma_f32 v[40:41], v[30:31], v[36:37], v[46:47] op_sel_hi:[1,0,1]
	v_mul_f32_e32 v30, v33, v33
	v_mul_f32_e32 v31, v35, v35
	v_pk_fma_f32 v[28:29], v[28:29], v[36:37], v[44:45] op_sel_hi:[1,0,1]
	v_fmac_f32_e32 v30, v32, v32
	v_fmac_f32_e32 v31, v34, v34
	v_add_f32_e32 v30, v30, v31
	v_mul_f32_e32 v31, v29, v29
	v_mul_f32_e32 v37, v41, v41
	v_fmac_f32_e32 v31, v28, v28
	v_fmac_f32_e32 v37, v40, v40
	v_add_f32_e32 v31, v31, v37
	v_add_f32_e32 v37, v30, v31
	v_cvt_pk_bf16_f32 v30, v32, v33
	v_cvt_pk_bf16_f32 v32, v28, v29
	v_lshl_add_u64 v[28:29], v[38:39], 1, s[64:65]
	v_cvt_pk_bf16_f32 v31, v34, v35
	v_cvt_pk_bf16_f32 v33, v40, v41
	v_lshl_add_u64 v[28:29], v[0:1], 1, v[28:29]
	global_store_dwordx4 v[28:29], v[30:33], off
	v_lshlrev_b32_e32 v34, 16, v78
	v_and_b32_e32 v35, 0xffff0000, v78
	v_lshlrev_b32_e32 v30, 16, v76
	v_and_b32_e32 v31, 0xffff0000, v76
	v_lshlrev_b32_e32 v32, 16, v77
	v_and_b32_e32 v33, 0xffff0000, v77
	v_lshlrev_b32_e32 v38, 16, v79
	v_and_b32_e32 v39, 0xffff0000, v79
	v_pk_fma_f32 v[26:27], v[26:27], v[36:37], v[32:33] op_sel_hi:[1,0,1]
	v_pk_fma_f32 v[24:25], v[24:25], v[36:37], v[30:31] op_sel_hi:[1,0,1]
	v_pk_fma_f32 v[30:31], v[22:23], v[36:37], v[38:39] op_sel_hi:[1,0,1]
	v_pk_fma_f32 v[22:23], v[20:21], v[36:37], v[34:35] op_sel_hi:[1,0,1]
	v_mul_f32_e32 v20, v25, v25
	v_mul_f32_e32 v21, v27, v27
	v_fmac_f32_e32 v20, v24, v24
	v_fmac_f32_e32 v21, v26, v26
	v_add_f32_e32 v20, v20, v21
	v_mul_f32_e32 v21, v23, v23
	v_mul_f32_e32 v32, v31, v31
	v_fmac_f32_e32 v21, v22, v22
	v_fmac_f32_e32 v32, v30, v30
	v_add_f32_e32 v21, v21, v32
	v_add_f32_e32 v20, v20, v21
	v_add_f32_e32 v32, v37, v20
	v_cvt_pk_bf16_f32 v20, v24, v25
	v_cvt_pk_bf16_f32 v21, v26, v27
	v_cvt_pk_bf16_f32 v22, v22, v23
	v_cvt_pk_bf16_f32 v23, v30, v31
	global_store_dwordx4 v[28:29], v[20:23], off offset:256
	ds_bpermute_b32 v20, v3, v32
	s_waitcnt lgkmcnt(0)
	v_add_f32_e32 v20, v32, v20
	ds_bpermute_b32 v21, v117, v20
	s_and_saveexec_b64 s[2:3], s[40:41]
	s_cbranch_execz .LBB0_945
	s_waitcnt lgkmcnt(0)
	v_add_f32_e32 v22, v20, v21
	v_floor_f32_e32 v24, v22
	v_sub_f32_e32 v22, v22, v24
	v_mul_f32_e32 v22, 0x4f800000, v22
	v_cvt_u32_f32_e32 v23, v24
	v_cvt_u32_f32_e32 v22, v22
	v_lshl_add_u64 v[20:21], v[98:99], 3, s[4:5]
	global_atomic_add_x2 v[20:21], v[22:23], off
.LBB0_945:
	s_or_b64 exec, exec, s[2:3]
	s_waitcnt lgkmcnt(0)
	s_nop 0
	v_mov_b32_e32 v25, v2
	v_lshlrev_b32_e32 v28, 16, v74
	v_and_b32_e32 v29, 0xffff0000, v74
	v_lshlrev_b32_e32 v30, 16, v75
	v_and_b32_e32 v31, 0xffff0000, v75
	v_lshlrev_b64 v[22:23], 11, v[96:97]
	v_mov_b32_e32 v20, v252
	s_nop 0
	s_nop 0
	s_nop 0
	s_nop 1
	s_nop 1
	s_nop 0
	v_lshlrev_b32_e32 v24, 16, v72
	v_and_b32_e32 v25, 0xffff0000, v72
	v_lshlrev_b32_e32 v26, 16, v73
	v_and_b32_e32 v27, 0xffff0000, v73
	v_pk_fma_f32 v[18:19], v[18:19], v[20:21], v[26:27] op_sel_hi:[1,0,1]
	v_pk_fma_f32 v[16:17], v[16:17], v[20:21], v[24:25] op_sel_hi:[1,0,1]
	v_pk_fma_f32 v[24:25], v[14:15], v[20:21], v[30:31] op_sel_hi:[1,0,1]
	v_pk_fma_f32 v[14:15], v[12:13], v[20:21], v[28:29] op_sel_hi:[1,0,1]
	v_mul_f32_e32 v12, v17, v17
	v_mul_f32_e32 v13, v19, v19
	v_fmac_f32_e32 v12, v16, v16
	v_fmac_f32_e32 v13, v18, v18
	v_add_f32_e32 v12, v12, v13
	v_mul_f32_e32 v13, v15, v15
	v_mul_f32_e32 v21, v25, v25
	v_fmac_f32_e32 v13, v14, v14
	v_fmac_f32_e32 v21, v24, v24
	v_add_f32_e32 v13, v13, v21
	v_add_f32_e32 v21, v12, v13
	v_cvt_pk_bf16_f32 v12, v16, v17
	v_lshl_add_u64 v[16:17], v[22:23], 1, s[64:65]
	v_cvt_pk_bf16_f32 v13, v18, v19
	v_cvt_pk_bf16_f32 v14, v14, v15
	v_cvt_pk_bf16_f32 v15, v24, v25
	v_lshl_add_u64 v[0:1], v[0:1], 1, v[16:17]
	global_store_dwordx4 v[0:1], v[12:15], off
	v_lshlrev_b32_e32 v16, 16, v70
	v_and_b32_e32 v17, 0xffff0000, v70
	v_lshlrev_b32_e32 v12, 16, v68
	v_and_b32_e32 v13, 0xffff0000, v68
	v_lshlrev_b32_e32 v14, 16, v69
	v_and_b32_e32 v15, 0xffff0000, v69
	v_lshlrev_b32_e32 v18, 16, v71
	v_and_b32_e32 v19, 0xffff0000, v71
	v_pk_fma_f32 v[10:11], v[10:11], v[20:21], v[14:15] op_sel_hi:[1,0,1]
	v_pk_fma_f32 v[8:9], v[8:9], v[20:21], v[12:13] op_sel_hi:[1,0,1]
	v_pk_fma_f32 v[12:13], v[6:7], v[20:21], v[18:19] op_sel_hi:[1,0,1]
	v_pk_fma_f32 v[6:7], v[4:5], v[20:21], v[16:17] op_sel_hi:[1,0,1]
	v_mul_f32_e32 v4, v9, v9
	v_mul_f32_e32 v5, v11, v11
	v_fmac_f32_e32 v4, v8, v8
	v_fmac_f32_e32 v5, v10, v10
	v_add_f32_e32 v4, v4, v5
	v_mul_f32_e32 v5, v7, v7
	v_mul_f32_e32 v14, v13, v13
	v_fmac_f32_e32 v5, v6, v6
	v_fmac_f32_e32 v14, v12, v12
	v_add_f32_e32 v5, v5, v14
	v_add_f32_e32 v4, v4, v5
	v_add_f32_e32 v14, v21, v4
	v_cvt_pk_bf16_f32 v4, v8, v9
	v_cvt_pk_bf16_f32 v5, v10, v11
	v_cvt_pk_bf16_f32 v6, v6, v7
	v_cvt_pk_bf16_f32 v7, v12, v13
	global_store_dwordx4 v[0:1], v[4:7], off offset:256
	ds_bpermute_b32 v0, v3, v14
	s_waitcnt lgkmcnt(0)
	v_add_f32_e32 v0, v14, v0
	ds_bpermute_b32 v1, v117, v0
	s_and_saveexec_b64 s[2:3], s[40:41]
	s_cbranch_execz .LBB0_947
	s_waitcnt lgkmcnt(0)
	v_add_f32_e32 v3, v0, v1
	v_floor_f32_e32 v4, v3
	v_sub_f32_e32 v3, v3, v4
	v_mul_f32_e32 v3, 0x4f800000, v3
	v_cvt_u32_f32_e32 v5, v4
	v_cvt_u32_f32_e32 v4, v3
	v_lshl_add_u64 v[0:1], v[96:97], 3, s[4:5]
	global_atomic_add_x2 v[0:1], v[4:5], off
